# v50 + lwdma (late-weights queue: LDS-DMA double-buffered fast path for w_ffn_gate/w_ffn_up chunks, next item's loads in flight during convert+store)
# baseline (speedup 1.0000x reference)
.LBB0_488:
	s_cmp_lt_u32 s7, 0x4800
	s_cbranch_scc1 .Llw_old
	s_cmp_lt_u32 s7, 0x9e00
	s_cbranch_scc1 .Llw_gate
	s_cmp_lt_u32 s7, 0xf400
	s_cbranch_scc1 .Llw_up

.Llw_gate:
	v_readlane_b32 s68, v254, 39
	v_readlane_b32 s69, v254, 40
	s_movk_i32 s77, 0x4800
	s_mov_b32 s78, 0
	s_branch .Llw_fast
.Llw_up:
	v_readlane_b32 s68, v254, 41
	v_readlane_b32 s69, v254, 42
	s_mov_b32 s77, 0x9e00
	s_mov_b32 s78, 0x100000
.Llw_fast:
	s_add_u32 s70, s58, 0x4c00000
	s_addc_u32 s71, s59, 0
	s_add_u32 s70, s70, s78
	s_addc_u32 s71, s71, 0
	s_lshl_b32 s72, s76, 14
	v_mbcnt_lo_u32_b32 v70, -1, 0
	v_mbcnt_hi_u32_b32 v70, -1, v70
	v_lshrrev_b32_e32 v71, 3, v70
	v_and_b32_e32 v72, 7, v70
	v_mul_u32_u24_e32 v73, 0xac00, v71
	v_xor_b32_e32 v74, 0, v72
	v_lshl_add_u32 v80, v74, 4, v73
	v_xor_b32_e32 v74, 1, v72
	v_lshl_add_u32 v81, v74, 4, v73
	v_add_u32_e32 v81, 0x56000, v81
	v_xor_b32_e32 v74, 2, v72
	v_lshl_add_u32 v82, v74, 4, v73
	v_add_u32_e32 v82, 0xac000, v82
	v_xor_b32_e32 v74, 3, v72
	v_lshl_add_u32 v83, v74, 4, v73
	v_add_u32_e32 v83, 0x102000, v83
	v_xor_b32_e32 v74, 4, v72
	v_lshl_add_u32 v84, v74, 4, v73
	v_add_u32_e32 v84, 0x158000, v84
	v_xor_b32_e32 v74, 5, v72
	v_lshl_add_u32 v85, v74, 4, v73
	v_add_u32_e32 v85, 0x1ae000, v85
	v_xor_b32_e32 v74, 6, v72
	v_lshl_add_u32 v86, v74, 4, v73
	v_add_u32_e32 v86, 0x204000, v86
	v_xor_b32_e32 v74, 7, v72
	v_lshl_add_u32 v87, v74, 4, v73
	v_add_u32_e32 v87, 0x25a000, v87
	v_lshlrev_b32_e32 v75, 10, v72
	v_lshrrev_b32_e32 v76, 5, v70
	v_and_b32_e32 v77, 3, v71
	v_lshlrev_b32_e32 v77, 2, v77
	v_add3_u32 v75, v75, v77, s72
	v_add_u32_e32 v74, 0, v76
	v_xor_b32_e32 v74, v74, v72
	v_lshl_add_u32 v88, v74, 4, v75
	v_add_u32_e32 v74, 2, v76
	v_xor_b32_e32 v74, v74, v72
	v_lshl_add_u32 v89, v74, 4, v75
	v_add_u32_e32 v74, 4, v76
	v_xor_b32_e32 v74, v74, v72
	v_lshl_add_u32 v90, v74, 4, v75
	v_add_u32_e32 v74, 6, v76
	v_xor_b32_e32 v74, v74, v72
	v_lshl_add_u32 v91, v74, 4, v75
	v_lshlrev_b32_e32 v92, 13, v71
	v_lshl_add_u32 v92, v72, 4, v92
	s_mov_b32 s73, s7
	s_mov_b32 s74, 0
	s_sub_i32 s60, s73, s77
	s_mul_i32 s61, s60, 0xbe83
	s_lshr_b32 s62, s61, 24
	s_mul_i32 s61, s62, 0x158
	s_sub_i32 s64, s60, s61
	s_mul_i32 s60, s62, 0x2b0000
	s_lshl_b32 s61, s64, 7
	s_add_u32 s60, s60, s61
	s_add_u32 s66, s68, s60
	s_addc_u32 s67, s69, 0
	s_add_i32 s65, s72, s74
	s_mov_b32 m0, s65
	s_nop 0
	global_load_lds_dwordx4 v80, s[66:67] nt
	s_add_i32 m0, s65, 0x400
	s_nop 0
	global_load_lds_dwordx4 v81, s[66:67] nt
	s_add_i32 m0, s65, 0x800
	s_nop 0
	global_load_lds_dwordx4 v82, s[66:67] nt
	s_add_i32 m0, s65, 0xc00
	s_nop 0
	global_load_lds_dwordx4 v83, s[66:67] nt
	s_add_i32 m0, s65, 0x1000
	s_nop 0
	global_load_lds_dwordx4 v84, s[66:67] nt
	s_add_i32 m0, s65, 0x1400
	s_nop 0
	global_load_lds_dwordx4 v85, s[66:67] nt
	s_add_i32 m0, s65, 0x1800
	s_nop 0
	global_load_lds_dwordx4 v86, s[66:67] nt
	s_add_i32 m0, s65, 0x1c00
	s_nop 0
	global_load_lds_dwordx4 v87, s[66:67] nt
	s_add_i32 s73, s73, 1
	s_mov_b32 s74, 0x2000
	s_cmp_lt_u32 s73, s6
	s_cbranch_scc0 .Llw_one
	s_sub_i32 s60, s73, s77
	s_mul_i32 s61, s60, 0xbe83
	s_lshr_b32 s62, s61, 24
	s_mul_i32 s61, s62, 0x158
	s_sub_i32 s64, s60, s61
	s_mul_i32 s60, s62, 0x2b0000
	s_lshl_b32 s61, s64, 7
	s_add_u32 s60, s60, s61
	s_add_u32 s66, s68, s60
	s_addc_u32 s67, s69, 0
	s_add_i32 s65, s72, s74
	s_mov_b32 m0, s65
	s_nop 0
	global_load_lds_dwordx4 v80, s[66:67] nt
	s_add_i32 m0, s65, 0x400
	s_nop 0
	global_load_lds_dwordx4 v81, s[66:67] nt
	s_add_i32 m0, s65, 0x800
	s_nop 0
	global_load_lds_dwordx4 v82, s[66:67] nt
	s_add_i32 m0, s65, 0xc00
	s_nop 0
	global_load_lds_dwordx4 v83, s[66:67] nt
	s_add_i32 m0, s65, 0x1000
	s_nop 0
	global_load_lds_dwordx4 v84, s[66:67] nt
	s_add_i32 m0, s65, 0x1400
	s_nop 0
	global_load_lds_dwordx4 v85, s[66:67] nt
	s_add_i32 m0, s65, 0x1800
	s_nop 0
	global_load_lds_dwordx4 v86, s[66:67] nt
	s_add_i32 m0, s65, 0x1c00
	s_nop 0
	global_load_lds_dwordx4 v87, s[66:67] nt
	s_add_i32 s73, s73, 1
	s_mov_b32 s74, 0
	s_mov_b32 s75, s7
	s_waitcnt vmcnt(8)
	s_branch .Llw_loop
.Llw_one:
	s_add_i32 s73, s73, 1
	s_mov_b32 s74, 0
	s_mov_b32 s75, s7
	s_waitcnt vmcnt(0)
.Llw_loop:
	s_sub_i32 s60, s73, 1
	s_cmp_lt_u32 s60, s6
	s_cbranch_scc1 .Llw_w12
	s_waitcnt vmcnt(4)
	s_branch .Llw_go

.Llw_go:
	ds_read2_b32 v[100:101], v88 offset0:0 offset1:32
	ds_read2_b32 v[102:103], v88 offset0:64 offset1:96
	ds_read2_b32 v[104:105], v88 offset0:128 offset1:160
	ds_read2_b32 v[106:107], v88 offset0:192 offset1:224
	ds_read2_b32 v[108:109], v89 offset0:0 offset1:32
	ds_read2_b32 v[110:111], v89 offset0:64 offset1:96
	ds_read2_b32 v[112:113], v89 offset0:128 offset1:160
	ds_read2_b32 v[114:115], v89 offset0:192 offset1:224
	ds_read2_b32 v[116:117], v90 offset0:0 offset1:32
	ds_read2_b32 v[118:119], v90 offset0:64 offset1:96
	ds_read2_b32 v[120:121], v90 offset0:128 offset1:160
	ds_read2_b32 v[122:123], v90 offset0:192 offset1:224
	ds_read2_b32 v[124:125], v91 offset0:0 offset1:32
	ds_read2_b32 v[126:127], v91 offset0:64 offset1:96
	ds_read2_b32 v[128:129], v91 offset0:128 offset1:160
	ds_read2_b32 v[130:131], v91 offset0:192 offset1:224
	s_sub_i32 s60, s75, s77
	s_mul_i32 s61, s60, 0xbe83
	s_lshr_b32 s62, s61, 24
	s_mul_i32 s61, s62, 0x158
	s_sub_i32 s64, s60, s61
	s_lshr_b32 s60, s64, 2
	s_lshl_b32 s60, s60, 8
	s_and_b32 s61, s64, 3
	s_lshl_b32 s61, s61, 5
	s_or_b32 s60, s60, s61
	s_lshl_b32 s60, s60, 13
	s_lshl_b32 s61, s62, 7
	s_add_u32 s60, s60, s61
	s_add_u32 s60, s70, s60
	s_addc_u32 s61, s71, 0
	s_waitcnt lgkmcnt(0)
	v_xor_b32_e32 v88, 0x2000, v88
	v_xor_b32_e32 v89, 0x2000, v89
	v_xor_b32_e32 v90, 0x2000, v90
	v_xor_b32_e32 v91, 0x2000, v91
	v_cvt_pk_bf16_f32 v132, v100, v101
	v_cvt_pk_bf16_f32 v133, v102, v103
	v_cvt_pk_bf16_f32 v134, v104, v105
	v_cvt_pk_bf16_f32 v135, v106, v107
	global_store_dwordx4 v92, v[132:135], s[60:61] nt
	s_add_u32 s60, s60, 0x10000
	s_addc_u32 s61, s61, 0
	s_nop 1
	v_cvt_pk_bf16_f32 v132, v108, v109
	v_cvt_pk_bf16_f32 v133, v110, v111
	v_cvt_pk_bf16_f32 v134, v112, v113
	v_cvt_pk_bf16_f32 v135, v114, v115
	global_store_dwordx4 v92, v[132:135], s[60:61] nt
	s_add_u32 s60, s60, 0x10000
	s_addc_u32 s61, s61, 0
	s_nop 1
	v_cvt_pk_bf16_f32 v132, v116, v117
	v_cvt_pk_bf16_f32 v133, v118, v119
	v_cvt_pk_bf16_f32 v134, v120, v121
	v_cvt_pk_bf16_f32 v135, v122, v123
	global_store_dwordx4 v92, v[132:135], s[60:61] nt
	s_add_u32 s60, s60, 0x10000
	s_addc_u32 s61, s61, 0
	s_nop 1
	v_cvt_pk_bf16_f32 v132, v124, v125
	v_cvt_pk_bf16_f32 v133, v126, v127
	v_cvt_pk_bf16_f32 v134, v128, v129
	v_cvt_pk_bf16_f32 v135, v130, v131
	global_store_dwordx4 v92, v[132:135], s[60:61] nt
	s_cmp_lt_u32 s73, s6
	s_cbranch_scc0 .Llw_noissue
	s_sub_i32 s60, s73, s77
	s_mul_i32 s61, s60, 0xbe83
	s_lshr_b32 s62, s61, 24
	s_mul_i32 s61, s62, 0x158
	s_sub_i32 s64, s60, s61
	s_mul_i32 s60, s62, 0x2b0000
	s_lshl_b32 s61, s64, 7
	s_add_u32 s60, s60, s61
	s_add_u32 s66, s68, s60
	s_addc_u32 s67, s69, 0
	s_add_i32 s65, s72, s74
	s_mov_b32 m0, s65
	s_nop 0
	global_load_lds_dwordx4 v80, s[66:67] nt
	s_add_i32 m0, s65, 0x400
	s_nop 0
	global_load_lds_dwordx4 v81, s[66:67] nt
	s_add_i32 m0, s65, 0x800
	s_nop 0
	global_load_lds_dwordx4 v82, s[66:67] nt
	s_add_i32 m0, s65, 0xc00
	s_nop 0
	global_load_lds_dwordx4 v83, s[66:67] nt
	s_add_i32 m0, s65, 0x1000
	s_nop 0
	global_load_lds_dwordx4 v84, s[66:67] nt
	s_add_i32 m0, s65, 0x1400
	s_nop 0
	global_load_lds_dwordx4 v85, s[66:67] nt
	s_add_i32 m0, s65, 0x1800
	s_nop 0
	global_load_lds_dwordx4 v86, s[66:67] nt
	s_add_i32 m0, s65, 0x1c00
	s_nop 0
	global_load_lds_dwordx4 v87, s[66:67] nt
.Llw_noissue:
	s_add_i32 s73, s73, 1
	s_xor_b32 s74, s74, 0x2000
	s_add_i32 s75, s75, 1
	s_cmp_lt_u32 s75, s6
	s_cbranch_scc1 .Llw_loop
	s_sub_i32 s7, s6, 1
	s_branch .LBB0_479
